# PH11a/b relu^2 epilogue rewritten by hand: 17 VALU per 16-byte store (was ~28), one base address + 32-bit adds
# speedup vs baseline: 1.0034x; 1.0034x over previous
; __device__ __forceinline__ int lane_id_asm() { int l; asm volatile("v_mbcnt_lo_u32_b32 %0, -1, 0\n\tv_mbcnt_hi_u32_b32 %0, -1, %0" : "=v"(l)); return l; }
; __device__ __forceinline__ u32x4 pack8(f32x4 a, f32x4 b) { u32x4 w; w.x = pk2(a[0], a[1]); w.y = pk2(a[2], a[3]); w.z = pk2(b[0], b[1]); w.w = pk2(b[2], b[3]); return w; }
;     __device__ __forceinline__ void operator()(const Acc& acc, const pg8::Unit& u, int wid) const {
;         const int lane_ = lane_id_asm(), wr = wid >> 2, wc = wid & 3, fr = lane_ & 15, fq = lane_ >> 4;
;         const int row0 = u.pm * 256 + wr * 64 + fr, col0 = u.pn * 256 + wc * 32 + 8 * fq;
;         float scv[8];
; #pragma unroll
;         for (int i = 0; i < 8; ++i) scv[i] = ssq ? ssq[row0 + (i >> 2) * 128 + (i & 3) * 16] : 0.f;
; #pragma unroll
;         for (int ai = 0; ai < 2; ++ai)
; #pragma unroll
;             for (int m = 0; m < 4; ++m) {
;                 const int row = row0 + ai * 128 + m * 16;
;                 const float sc = ssq ? __builtin_amdgcn_rsqf(scv[ai * 4 + m] * inv_n + EPS) : 1.f;
; #pragma unroll
;                 for (int bj = 0; bj < 2; ++bj) {
;                     f32x4 v0 = acc[ai][bj][m][0] * sc, v1 = acc[ai][bj][m][1] * sc;
;                     if (ACT == 1) {
; #pragma unroll
;                         for (int e = 0; e < 4; ++e) { float a = fmaxf(v0[e], 0.f), b = fmaxf(v1[e], 0.f); v0[e] = a * a; v1[e] = b * b; }
;                     }
;                     *(u32x4*)(O + (size_t)row * ldc + col0 + bj * 128) = pack8(v0, v1);
.LBB0_488:
	s_lshl_b32 s4, s34, 8
	v_mbcnt_lo_u32_b32 v149, -1, 0
	v_mbcnt_hi_u32_b32 v149, -1, v149
	s_add_i32 s4, s4, s77
	v_and_or_b32 v148, v149, 15, s4
	v_ashrrev_i32_e32 v149, 1, v149
	s_lshl_b32 s4, s89, 8
	v_and_b32_e32 v149, -8, v149
	s_or_b32 s4, s4, s69
	v_add_u32_e32 v150, s4, v149
	v_mov_b32_e32 v149, 0
	v_mov_b32_e32 v151, 0
	v_lshlrev_b64 v[152:153], 13, v[148:149]
	v_lshl_add_u64 v[152:153], s[44:45], 0, v[152:153]
	v_lshlrev_b64 v[150:151], 1, v[150:151]
	v_lshl_add_u64 v[152:153], v[152:153], 0, v[150:151]
	v_max_f32_e32 v124, 0, v124
	v_max_f32_e32 v125, 0, v125
	v_max_f32_e32 v126, 0, v126
	v_max_f32_e32 v127, 0, v127
	v_max_f32_e32 v120, 0, v120
	v_max_f32_e32 v121, 0, v121
	v_max_f32_e32 v122, 0, v122
	v_max_f32_e32 v123, 0, v123
	v_pk_mul_f32 v[124:125], v[124:125], v[124:125]
	v_pk_mul_f32 v[126:127], v[126:127], v[126:127]
	v_pk_mul_f32 v[120:121], v[120:121], v[120:121]
	v_pk_mul_f32 v[122:123], v[122:123], v[122:123]
	v_cvt_pk_bf16_f32 v124, v124, v125
	v_cvt_pk_bf16_f32 v125, v126, v127
	v_cvt_pk_bf16_f32 v126, v120, v121
	v_cvt_pk_bf16_f32 v127, v122, v123
	flat_store_dwordx4 v[152:153], v[124:127]
	v_max_f32_e32 v116, 0, v116
	v_max_f32_e32 v117, 0, v117
	v_max_f32_e32 v118, 0, v118
	v_max_f32_e32 v119, 0, v119
	v_max_f32_e32 v112, 0, v112
	v_max_f32_e32 v113, 0, v113
	v_max_f32_e32 v114, 0, v114
	v_max_f32_e32 v115, 0, v115
	v_pk_mul_f32 v[116:117], v[116:117], v[116:117]
	v_pk_mul_f32 v[118:119], v[118:119], v[118:119]
	v_pk_mul_f32 v[112:113], v[112:113], v[112:113]
	v_pk_mul_f32 v[114:115], v[114:115], v[114:115]
	v_cvt_pk_bf16_f32 v116, v116, v117
	v_cvt_pk_bf16_f32 v117, v118, v119
	v_cvt_pk_bf16_f32 v118, v112, v113
	v_cvt_pk_bf16_f32 v119, v114, v115
	flat_store_dwordx4 v[152:153], v[116:119] offset:256
	v_add_co_u32_e32 v150, vcc, 0x20000, v152
	s_nop 1
	v_addc_co_u32_e32 v151, vcc, 0, v153, vcc
	v_max_f32_e32 v108, 0, v108
	v_max_f32_e32 v109, 0, v109
	v_max_f32_e32 v110, 0, v110
	v_max_f32_e32 v111, 0, v111
	v_max_f32_e32 v104, 0, v104
	v_max_f32_e32 v105, 0, v105
	v_max_f32_e32 v106, 0, v106
	v_max_f32_e32 v107, 0, v107
	v_pk_mul_f32 v[108:109], v[108:109], v[108:109]
	v_pk_mul_f32 v[110:111], v[110:111], v[110:111]
	v_pk_mul_f32 v[104:105], v[104:105], v[104:105]
	v_pk_mul_f32 v[106:107], v[106:107], v[106:107]
	v_cvt_pk_bf16_f32 v108, v108, v109
	v_cvt_pk_bf16_f32 v109, v110, v111
	v_cvt_pk_bf16_f32 v110, v104, v105
	v_cvt_pk_bf16_f32 v111, v106, v107
	flat_store_dwordx4 v[150:151], v[108:111]
	v_max_f32_e32 v100, 0, v100
	v_max_f32_e32 v101, 0, v101
	v_max_f32_e32 v102, 0, v102
	v_max_f32_e32 v103, 0, v103
	v_max_f32_e32 v96, 0, v96
	v_max_f32_e32 v97, 0, v97
	v_max_f32_e32 v98, 0, v98
	v_max_f32_e32 v99, 0, v99
	v_pk_mul_f32 v[100:101], v[100:101], v[100:101]
	v_pk_mul_f32 v[102:103], v[102:103], v[102:103]
	v_pk_mul_f32 v[96:97], v[96:97], v[96:97]
	v_pk_mul_f32 v[98:99], v[98:99], v[98:99]
	v_cvt_pk_bf16_f32 v100, v100, v101
	v_cvt_pk_bf16_f32 v101, v102, v103
	v_cvt_pk_bf16_f32 v102, v96, v97
	v_cvt_pk_bf16_f32 v103, v98, v99
	flat_store_dwordx4 v[150:151], v[100:103] offset:256
	v_add_co_u32_e32 v150, vcc, 0x40000, v152
	s_nop 1
	v_addc_co_u32_e32 v151, vcc, 0, v153, vcc
	v_max_f32_e32 v92, 0, v92
	v_max_f32_e32 v93, 0, v93
	v_max_f32_e32 v94, 0, v94
	v_max_f32_e32 v95, 0, v95
	v_max_f32_e32 v88, 0, v88
	v_max_f32_e32 v89, 0, v89
	v_max_f32_e32 v90, 0, v90
	v_max_f32_e32 v91, 0, v91
	v_pk_mul_f32 v[92:93], v[92:93], v[92:93]
	v_pk_mul_f32 v[94:95], v[94:95], v[94:95]
	v_pk_mul_f32 v[88:89], v[88:89], v[88:89]
	v_pk_mul_f32 v[90:91], v[90:91], v[90:91]
	v_cvt_pk_bf16_f32 v92, v92, v93
	v_cvt_pk_bf16_f32 v93, v94, v95
	v_cvt_pk_bf16_f32 v94, v88, v89
	v_cvt_pk_bf16_f32 v95, v90, v91
	flat_store_dwordx4 v[150:151], v[92:95]
	v_max_f32_e32 v84, 0, v84
	v_max_f32_e32 v85, 0, v85
	v_max_f32_e32 v86, 0, v86
	v_max_f32_e32 v87, 0, v87
	v_max_f32_e32 v80, 0, v80
	v_max_f32_e32 v81, 0, v81
	v_max_f32_e32 v82, 0, v82
	v_max_f32_e32 v83, 0, v83
	v_pk_mul_f32 v[84:85], v[84:85], v[84:85]
	v_pk_mul_f32 v[86:87], v[86:87], v[86:87]
	v_pk_mul_f32 v[80:81], v[80:81], v[80:81]
	v_pk_mul_f32 v[82:83], v[82:83], v[82:83]
	v_cvt_pk_bf16_f32 v84, v84, v85
	v_cvt_pk_bf16_f32 v85, v86, v87
	v_cvt_pk_bf16_f32 v86, v80, v81
	v_cvt_pk_bf16_f32 v87, v82, v83
	flat_store_dwordx4 v[150:151], v[84:87] offset:256
	v_add_co_u32_e32 v150, vcc, 0x60000, v152
	s_nop 1
	v_addc_co_u32_e32 v151, vcc, 0, v153, vcc
	v_max_f32_e32 v76, 0, v76
	v_max_f32_e32 v77, 0, v77
	v_max_f32_e32 v78, 0, v78
	v_max_f32_e32 v79, 0, v79
	v_max_f32_e32 v72, 0, v72
	v_max_f32_e32 v73, 0, v73
	v_max_f32_e32 v74, 0, v74
	v_max_f32_e32 v75, 0, v75
	v_pk_mul_f32 v[76:77], v[76:77], v[76:77]
	v_pk_mul_f32 v[78:79], v[78:79], v[78:79]
	v_pk_mul_f32 v[72:73], v[72:73], v[72:73]
	v_pk_mul_f32 v[74:75], v[74:75], v[74:75]
	v_cvt_pk_bf16_f32 v76, v76, v77
	v_cvt_pk_bf16_f32 v77, v78, v79
	v_cvt_pk_bf16_f32 v78, v72, v73
	v_cvt_pk_bf16_f32 v79, v74, v75
	flat_store_dwordx4 v[150:151], v[76:79]
	v_max_f32_e32 v68, 0, v68
	v_max_f32_e32 v69, 0, v69
	v_max_f32_e32 v70, 0, v70
	v_max_f32_e32 v71, 0, v71
	v_max_f32_e32 v64, 0, v64
	v_max_f32_e32 v65, 0, v65
	v_max_f32_e32 v66, 0, v66
	v_max_f32_e32 v67, 0, v67
	v_pk_mul_f32 v[68:69], v[68:69], v[68:69]
	v_pk_mul_f32 v[70:71], v[70:71], v[70:71]
; __device__ __forceinline__ u32x4 pack8(f32x4 a, f32x4 b) { u32x4 w; w.x = pk2(a[0], a[1]); w.y = pk2(a[2], a[3]); w.z = pk2(b[0], b[1]); w.w = pk2(b[2], b[3]); return w; }
;     __device__ __forceinline__ void operator()(const Acc& acc, const pg8::Unit& u, int wid) const {
;     ...
; #pragma unroll
;         for (int ai = 0; ai < 2; ++ai)
; #pragma unroll
;             for (int m = 0; m < 4; ++m) {
;                 const int row = row0 + ai * 128 + m * 16;
;                 const float sc = ssq ? __builtin_amdgcn_rsqf(scv[ai * 4 + m] * inv_n + EPS) : 1.f;
; #pragma unroll
;                 for (int bj = 0; bj < 2; ++bj) {
;                     f32x4 v0 = acc[ai][bj][m][0] * sc, v1 = acc[ai][bj][m][1] * sc;
;                     if (ACT == 1) {
; #pragma unroll
;                         for (int e = 0; e < 4; ++e) { float a = fmaxf(v0[e], 0.f), b = fmaxf(v1[e], 0.f); v0[e] = a * a; v1[e] = b * b; }
;                     }
;                     *(u32x4*)(O + (size_t)row * ldc + col0 + bj * 128) = pack8(v0, v1);
	v_pk_mul_f32 v[64:65], v[64:65], v[64:65]
	v_pk_mul_f32 v[66:67], v[66:67], v[66:67]
	v_cvt_pk_bf16_f32 v68, v68, v69
	v_cvt_pk_bf16_f32 v69, v70, v71
	v_cvt_pk_bf16_f32 v70, v64, v65
	v_cvt_pk_bf16_f32 v71, v66, v67
	flat_store_dwordx4 v[150:151], v[68:71] offset:256
	v_add_co_u32_e32 v150, vcc, 0x100000, v152
	s_nop 1
	v_addc_co_u32_e32 v151, vcc, 0, v153, vcc
	v_max_f32_e32 v60, 0, v60
	v_max_f32_e32 v61, 0, v61
	v_max_f32_e32 v62, 0, v62
	v_max_f32_e32 v63, 0, v63
	v_max_f32_e32 v56, 0, v56
	v_max_f32_e32 v57, 0, v57
	v_max_f32_e32 v58, 0, v58
	v_max_f32_e32 v59, 0, v59
	v_pk_mul_f32 v[60:61], v[60:61], v[60:61]
	v_pk_mul_f32 v[62:63], v[62:63], v[62:63]
	v_pk_mul_f32 v[56:57], v[56:57], v[56:57]
	v_pk_mul_f32 v[58:59], v[58:59], v[58:59]
	v_cvt_pk_bf16_f32 v60, v60, v61
	v_cvt_pk_bf16_f32 v61, v62, v63
	v_cvt_pk_bf16_f32 v62, v56, v57
	v_cvt_pk_bf16_f32 v63, v58, v59
	flat_store_dwordx4 v[150:151], v[60:63]
	v_max_f32_e32 v52, 0, v52
	v_max_f32_e32 v53, 0, v53
	v_max_f32_e32 v54, 0, v54
	v_max_f32_e32 v55, 0, v55
	v_max_f32_e32 v48, 0, v48
	v_max_f32_e32 v49, 0, v49
	v_max_f32_e32 v50, 0, v50
	v_max_f32_e32 v51, 0, v51
	v_pk_mul_f32 v[52:53], v[52:53], v[52:53]
	v_pk_mul_f32 v[54:55], v[54:55], v[54:55]
	v_pk_mul_f32 v[48:49], v[48:49], v[48:49]
	v_pk_mul_f32 v[50:51], v[50:51], v[50:51]
	v_cvt_pk_bf16_f32 v52, v52, v53
	v_cvt_pk_bf16_f32 v53, v54, v55
	v_cvt_pk_bf16_f32 v54, v48, v49
	v_cvt_pk_bf16_f32 v55, v50, v51
	flat_store_dwordx4 v[150:151], v[52:55] offset:256
	v_add_co_u32_e32 v150, vcc, 0x120000, v152
	s_nop 1
	v_addc_co_u32_e32 v151, vcc, 0, v153, vcc
	v_max_f32_e32 v44, 0, v44
	v_max_f32_e32 v45, 0, v45
	v_max_f32_e32 v46, 0, v46
	v_max_f32_e32 v47, 0, v47
	v_max_f32_e32 v40, 0, v40
	v_max_f32_e32 v41, 0, v41
	v_max_f32_e32 v42, 0, v42
	v_max_f32_e32 v43, 0, v43
	v_pk_mul_f32 v[44:45], v[44:45], v[44:45]
	v_pk_mul_f32 v[46:47], v[46:47], v[46:47]
	v_pk_mul_f32 v[40:41], v[40:41], v[40:41]
	v_pk_mul_f32 v[42:43], v[42:43], v[42:43]
	v_cvt_pk_bf16_f32 v44, v44, v45
	v_cvt_pk_bf16_f32 v45, v46, v47
	v_cvt_pk_bf16_f32 v46, v40, v41
	v_cvt_pk_bf16_f32 v47, v42, v43
	flat_store_dwordx4 v[150:151], v[44:47]
	v_max_f32_e32 v36, 0, v36
	v_max_f32_e32 v37, 0, v37
	v_max_f32_e32 v38, 0, v38
	v_max_f32_e32 v39, 0, v39
	v_max_f32_e32 v32, 0, v32
	v_max_f32_e32 v33, 0, v33
	v_max_f32_e32 v34, 0, v34
	v_max_f32_e32 v35, 0, v35
	v_pk_mul_f32 v[36:37], v[36:37], v[36:37]
	v_pk_mul_f32 v[38:39], v[38:39], v[38:39]
	v_pk_mul_f32 v[32:33], v[32:33], v[32:33]
	v_pk_mul_f32 v[34:35], v[34:35], v[34:35]
	v_cvt_pk_bf16_f32 v36, v36, v37
	v_cvt_pk_bf16_f32 v37, v38, v39
	v_cvt_pk_bf16_f32 v38, v32, v33
	v_cvt_pk_bf16_f32 v39, v34, v35
	flat_store_dwordx4 v[150:151], v[36:39] offset:256
	v_add_co_u32_e32 v150, vcc, 0x140000, v152
	s_nop 1
	v_addc_co_u32_e32 v151, vcc, 0, v153, vcc
	v_max_f32_e32 v28, 0, v28
	v_max_f32_e32 v29, 0, v29
	v_max_f32_e32 v30, 0, v30
	v_max_f32_e32 v31, 0, v31
	v_max_f32_e32 v24, 0, v24
	v_max_f32_e32 v25, 0, v25
	v_max_f32_e32 v26, 0, v26
	v_max_f32_e32 v27, 0, v27
	v_pk_mul_f32 v[28:29], v[28:29], v[28:29]
	v_pk_mul_f32 v[30:31], v[30:31], v[30:31]
	v_pk_mul_f32 v[24:25], v[24:25], v[24:25]
	v_pk_mul_f32 v[26:27], v[26:27], v[26:27]
	v_cvt_pk_bf16_f32 v28, v28, v29
	v_cvt_pk_bf16_f32 v29, v30, v31
	v_cvt_pk_bf16_f32 v30, v24, v25
	v_cvt_pk_bf16_f32 v31, v26, v27
	flat_store_dwordx4 v[150:151], v[28:31]
	v_max_f32_e32 v20, 0, v20
	v_max_f32_e32 v21, 0, v21
	v_max_f32_e32 v22, 0, v22
	v_max_f32_e32 v23, 0, v23
	v_max_f32_e32 v16, 0, v16
	v_max_f32_e32 v17, 0, v17
	v_max_f32_e32 v18, 0, v18
	v_max_f32_e32 v19, 0, v19
	v_pk_mul_f32 v[20:21], v[20:21], v[20:21]
	v_pk_mul_f32 v[22:23], v[22:23], v[22:23]
	v_pk_mul_f32 v[16:17], v[16:17], v[16:17]
	v_pk_mul_f32 v[18:19], v[18:19], v[18:19]
	v_cvt_pk_bf16_f32 v20, v20, v21
	v_cvt_pk_bf16_f32 v21, v22, v23
	v_cvt_pk_bf16_f32 v22, v16, v17
	v_cvt_pk_bf16_f32 v23, v18, v19
	flat_store_dwordx4 v[150:151], v[20:23] offset:256
	v_add_co_u32_e32 v150, vcc, 0x160000, v152
	s_nop 1
	v_addc_co_u32_e32 v151, vcc, 0, v153, vcc
	v_max_f32_e32 v12, 0, v12
	v_max_f32_e32 v13, 0, v13
	v_max_f32_e32 v14, 0, v14
	v_max_f32_e32 v15, 0, v15
	v_max_f32_e32 v8, 0, v8
	v_max_f32_e32 v9, 0, v9
	v_max_f32_e32 v10, 0, v10
	v_max_f32_e32 v11, 0, v11
	v_pk_mul_f32 v[12:13], v[12:13], v[12:13]
	v_pk_mul_f32 v[14:15], v[14:15], v[14:15]
	v_pk_mul_f32 v[8:9], v[8:9], v[8:9]
	v_pk_mul_f32 v[10:11], v[10:11], v[10:11]
	v_cvt_pk_bf16_f32 v12, v12, v13
	v_cvt_pk_bf16_f32 v13, v14, v15
	v_cvt_pk_bf16_f32 v14, v8, v9
	v_cvt_pk_bf16_f32 v15, v10, v11
	flat_store_dwordx4 v[150:151], v[12:15]
	v_max_f32_e32 v4, 0, v4
	v_max_f32_e32 v5, 0, v5
	v_max_f32_e32 v6, 0, v6
	v_max_f32_e32 v7, 0, v7
	v_max_f32_e32 v0, 0, v0
	v_max_f32_e32 v1, 0, v1
	v_max_f32_e32 v2, 0, v2
	v_max_f32_e32 v3, 0, v3
	v_pk_mul_f32 v[4:5], v[4:5], v[4:5]
	v_pk_mul_f32 v[6:7], v[6:7], v[6:7]
	v_pk_mul_f32 v[0:1], v[0:1], v[0:1]
	v_pk_mul_f32 v[2:3], v[2:3], v[2:3]
	v_cvt_pk_bf16_f32 v4, v4, v5
	v_cvt_pk_bf16_f32 v5, v6, v7
	v_cvt_pk_bf16_f32 v6, v0, v1
	v_cvt_pk_bf16_f32 v7, v2, v3
	s_andn2_b64 vcc, exec, s[6:7]
	s_mov_b64 s[6:7], -1
	flat_store_dwordx4 v[150:151], v[4:7] offset:256
	s_cbranch_vccnz .LBB0_477
	s_andn2_b64 vcc, exec, s[0:1]
	s_cbranch_vccnz .LBB0_476
	s_barrier
	s_branch .LBB0_476

; __device__ __forceinline__ int lane_id_asm() { int l; asm volatile("v_mbcnt_lo_u32_b32 %0, -1, 0\n\tv_mbcnt_hi_u32_b32 %0, -1, %0" : "=v"(l)); return l; }
; __device__ __forceinline__ u32x4 pack8(f32x4 a, f32x4 b) { u32x4 w; w.x = pk2(a[0], a[1]); w.y = pk2(a[2], a[3]); w.z = pk2(b[0], b[1]); w.w = pk2(b[2], b[3]); return w; }
;     __device__ __forceinline__ void operator()(const Acc& acc, const pg8::Unit& u, int wid) const {
;         const int lane_ = lane_id_asm(), wr = wid >> 2, wc = wid & 3, fr = lane_ & 15, fq = lane_ >> 4;
;         const int row0 = u.pm * 256 + wr * 64 + fr, col0 = u.pn * 256 + wc * 32 + 8 * fq;
;         float scv[8];
; #pragma unroll
;         for (int i = 0; i < 8; ++i) scv[i] = ssq ? ssq[row0 + (i >> 2) * 128 + (i & 3) * 16] : 0.f;
; #pragma unroll
;         for (int ai = 0; ai < 2; ++ai)
; #pragma unroll
;             for (int m = 0; m < 4; ++m) {
;                 const int row = row0 + ai * 128 + m * 16;
;                 const float sc = ssq ? __builtin_amdgcn_rsqf(scv[ai * 4 + m] * inv_n + EPS) : 1.f;
; #pragma unroll
;                 for (int bj = 0; bj < 2; ++bj) {
;                     f32x4 v0 = acc[ai][bj][m][0] * sc, v1 = acc[ai][bj][m][1] * sc;
;                     if (ACT == 1) {
; #pragma unroll
;                         for (int e = 0; e < 4; ++e) { float a = fmaxf(v0[e], 0.f), b = fmaxf(v1[e], 0.f); v0[e] = a * a; v1[e] = b * b; }
;                     }
;                     *(u32x4*)(O + (size_t)row * ldc + col0 + bj * 128) = pack8(v0, v1);
.LBB0_1178:
	s_lshl_b32 s23, s30, 8
	v_mbcnt_lo_u32_b32 v149, -1, 0
	v_mbcnt_hi_u32_b32 v149, -1, v149
	s_add_i32 s23, s23, s65
	v_and_or_b32 v148, v149, 15, s23
	v_ashrrev_i32_e32 v149, 1, v149
	s_lshl_b32 s23, s79, 8
	v_and_b32_e32 v149, -8, v149
	s_or_b32 s23, s23, s69
	v_add_u32_e32 v150, s23, v149
	v_mov_b32_e32 v149, 0
	v_mov_b32_e32 v151, 0
	v_lshlrev_b64 v[152:153], 13, v[148:149]
	v_lshl_add_u64 v[152:153], s[44:45], 0, v[152:153]
	v_lshlrev_b64 v[150:151], 1, v[150:151]
	v_lshl_add_u64 v[152:153], v[152:153], 0, v[150:151]
	v_max_f32_e32 v124, 0, v124
	v_max_f32_e32 v125, 0, v125
	v_max_f32_e32 v126, 0, v126
	v_max_f32_e32 v127, 0, v127
	v_max_f32_e32 v120, 0, v120
	v_max_f32_e32 v121, 0, v121
	v_max_f32_e32 v122, 0, v122
	v_max_f32_e32 v123, 0, v123
	v_pk_mul_f32 v[124:125], v[124:125], v[124:125]
	v_pk_mul_f32 v[126:127], v[126:127], v[126:127]
	v_pk_mul_f32 v[120:121], v[120:121], v[120:121]
	v_pk_mul_f32 v[122:123], v[122:123], v[122:123]
	v_cvt_pk_bf16_f32 v124, v124, v125
	v_cvt_pk_bf16_f32 v125, v126, v127
	v_cvt_pk_bf16_f32 v126, v120, v121
	v_cvt_pk_bf16_f32 v127, v122, v123
	flat_store_dwordx4 v[152:153], v[124:127]
	v_max_f32_e32 v116, 0, v116
	v_max_f32_e32 v117, 0, v117
	v_max_f32_e32 v118, 0, v118
	v_max_f32_e32 v119, 0, v119
	v_max_f32_e32 v112, 0, v112
	v_max_f32_e32 v113, 0, v113
	v_max_f32_e32 v114, 0, v114
	v_max_f32_e32 v115, 0, v115
	v_pk_mul_f32 v[116:117], v[116:117], v[116:117]
	v_pk_mul_f32 v[118:119], v[118:119], v[118:119]
	v_pk_mul_f32 v[112:113], v[112:113], v[112:113]
	v_pk_mul_f32 v[114:115], v[114:115], v[114:115]
	v_cvt_pk_bf16_f32 v116, v116, v117
	v_cvt_pk_bf16_f32 v117, v118, v119
	v_cvt_pk_bf16_f32 v118, v112, v113
	v_cvt_pk_bf16_f32 v119, v114, v115
	flat_store_dwordx4 v[152:153], v[116:119] offset:256
	v_add_co_u32_e32 v150, vcc, 0x20000, v152
	s_nop 1
	v_addc_co_u32_e32 v151, vcc, 0, v153, vcc
	v_max_f32_e32 v108, 0, v108
	v_max_f32_e32 v109, 0, v109
	v_max_f32_e32 v110, 0, v110
	v_max_f32_e32 v111, 0, v111
	v_max_f32_e32 v104, 0, v104
	v_max_f32_e32 v105, 0, v105
	v_max_f32_e32 v106, 0, v106
	v_max_f32_e32 v107, 0, v107
	v_pk_mul_f32 v[108:109], v[108:109], v[108:109]
	v_pk_mul_f32 v[110:111], v[110:111], v[110:111]
	v_pk_mul_f32 v[104:105], v[104:105], v[104:105]
	v_pk_mul_f32 v[106:107], v[106:107], v[106:107]
	v_cvt_pk_bf16_f32 v108, v108, v109
	v_cvt_pk_bf16_f32 v109, v110, v111
	v_cvt_pk_bf16_f32 v110, v104, v105
	v_cvt_pk_bf16_f32 v111, v106, v107
	flat_store_dwordx4 v[150:151], v[108:111]
	v_max_f32_e32 v100, 0, v100
	v_max_f32_e32 v101, 0, v101
	v_max_f32_e32 v102, 0, v102
	v_max_f32_e32 v103, 0, v103
	v_max_f32_e32 v96, 0, v96
	v_max_f32_e32 v97, 0, v97
	v_max_f32_e32 v98, 0, v98
	v_max_f32_e32 v99, 0, v99
	v_pk_mul_f32 v[100:101], v[100:101], v[100:101]
	v_pk_mul_f32 v[102:103], v[102:103], v[102:103]
	v_pk_mul_f32 v[96:97], v[96:97], v[96:97]
	v_pk_mul_f32 v[98:99], v[98:99], v[98:99]
	v_cvt_pk_bf16_f32 v100, v100, v101
	v_cvt_pk_bf16_f32 v101, v102, v103
	v_cvt_pk_bf16_f32 v102, v96, v97
	v_cvt_pk_bf16_f32 v103, v98, v99
	flat_store_dwordx4 v[150:151], v[100:103] offset:256
	v_add_co_u32_e32 v150, vcc, 0x40000, v152
	s_nop 1
	v_addc_co_u32_e32 v151, vcc, 0, v153, vcc
	v_max_f32_e32 v92, 0, v92
	v_max_f32_e32 v93, 0, v93
	v_max_f32_e32 v94, 0, v94
	v_max_f32_e32 v95, 0, v95
	v_max_f32_e32 v88, 0, v88
	v_max_f32_e32 v89, 0, v89
	v_max_f32_e32 v90, 0, v90
	v_max_f32_e32 v91, 0, v91
	v_pk_mul_f32 v[92:93], v[92:93], v[92:93]
	v_pk_mul_f32 v[94:95], v[94:95], v[94:95]
	v_pk_mul_f32 v[88:89], v[88:89], v[88:89]
	v_pk_mul_f32 v[90:91], v[90:91], v[90:91]
	v_cvt_pk_bf16_f32 v92, v92, v93
	v_cvt_pk_bf16_f32 v93, v94, v95
	v_cvt_pk_bf16_f32 v94, v88, v89
	v_cvt_pk_bf16_f32 v95, v90, v91
	flat_store_dwordx4 v[150:151], v[92:95]
	v_max_f32_e32 v84, 0, v84
	v_max_f32_e32 v85, 0, v85
	v_max_f32_e32 v86, 0, v86
	v_max_f32_e32 v87, 0, v87
	v_max_f32_e32 v80, 0, v80
	v_max_f32_e32 v81, 0, v81
	v_max_f32_e32 v82, 0, v82
	v_max_f32_e32 v83, 0, v83
	v_pk_mul_f32 v[84:85], v[84:85], v[84:85]
	v_pk_mul_f32 v[86:87], v[86:87], v[86:87]
	v_pk_mul_f32 v[80:81], v[80:81], v[80:81]
	v_pk_mul_f32 v[82:83], v[82:83], v[82:83]
	v_cvt_pk_bf16_f32 v84, v84, v85
	v_cvt_pk_bf16_f32 v85, v86, v87
	v_cvt_pk_bf16_f32 v86, v80, v81
	v_cvt_pk_bf16_f32 v87, v82, v83
	flat_store_dwordx4 v[150:151], v[84:87] offset:256
	v_add_co_u32_e32 v150, vcc, 0x60000, v152
	s_nop 1
	v_addc_co_u32_e32 v151, vcc, 0, v153, vcc
	v_max_f32_e32 v76, 0, v76
	v_max_f32_e32 v77, 0, v77
	v_max_f32_e32 v78, 0, v78
	v_max_f32_e32 v79, 0, v79
	v_max_f32_e32 v72, 0, v72
	v_max_f32_e32 v73, 0, v73
	v_max_f32_e32 v74, 0, v74
	v_max_f32_e32 v75, 0, v75
	v_pk_mul_f32 v[76:77], v[76:77], v[76:77]
	v_pk_mul_f32 v[78:79], v[78:79], v[78:79]
	v_pk_mul_f32 v[72:73], v[72:73], v[72:73]
	v_pk_mul_f32 v[74:75], v[74:75], v[74:75]
	v_cvt_pk_bf16_f32 v76, v76, v77
	v_cvt_pk_bf16_f32 v77, v78, v79
	v_cvt_pk_bf16_f32 v78, v72, v73
	v_cvt_pk_bf16_f32 v79, v74, v75
	flat_store_dwordx4 v[150:151], v[76:79]
	v_max_f32_e32 v68, 0, v68
	v_max_f32_e32 v69, 0, v69
	v_max_f32_e32 v70, 0, v70
	v_max_f32_e32 v71, 0, v71
	v_max_f32_e32 v64, 0, v64
	v_max_f32_e32 v65, 0, v65
	v_max_f32_e32 v66, 0, v66
	v_max_f32_e32 v67, 0, v67
	v_pk_mul_f32 v[68:69], v[68:69], v[68:69]
	v_pk_mul_f32 v[70:71], v[70:71], v[70:71]
; __device__ __forceinline__ u32x4 pack8(f32x4 a, f32x4 b) { u32x4 w; w.x = pk2(a[0], a[1]); w.y = pk2(a[2], a[3]); w.z = pk2(b[0], b[1]); w.w = pk2(b[2], b[3]); return w; }
;     __device__ __forceinline__ void operator()(const Acc& acc, const pg8::Unit& u, int wid) const {
;     ...
; #pragma unroll
;         for (int ai = 0; ai < 2; ++ai)
; #pragma unroll
;             for (int m = 0; m < 4; ++m) {
;                 const int row = row0 + ai * 128 + m * 16;
;                 const float sc = ssq ? __builtin_amdgcn_rsqf(scv[ai * 4 + m] * inv_n + EPS) : 1.f;
; #pragma unroll
;                 for (int bj = 0; bj < 2; ++bj) {
;                     f32x4 v0 = acc[ai][bj][m][0] * sc, v1 = acc[ai][bj][m][1] * sc;
;                     if (ACT == 1) {
; #pragma unroll
;                         for (int e = 0; e < 4; ++e) { float a = fmaxf(v0[e], 0.f), b = fmaxf(v1[e], 0.f); v0[e] = a * a; v1[e] = b * b; }
;                     }
;                     *(u32x4*)(O + (size_t)row * ldc + col0 + bj * 128) = pack8(v0, v1);
	v_pk_mul_f32 v[64:65], v[64:65], v[64:65]
	v_pk_mul_f32 v[66:67], v[66:67], v[66:67]
	v_cvt_pk_bf16_f32 v68, v68, v69
	v_cvt_pk_bf16_f32 v69, v70, v71
	v_cvt_pk_bf16_f32 v70, v64, v65
	v_cvt_pk_bf16_f32 v71, v66, v67
	flat_store_dwordx4 v[150:151], v[68:71] offset:256
	v_add_co_u32_e32 v150, vcc, 0x100000, v152
	s_nop 1
	v_addc_co_u32_e32 v151, vcc, 0, v153, vcc
	v_max_f32_e32 v60, 0, v60
	v_max_f32_e32 v61, 0, v61
	v_max_f32_e32 v62, 0, v62
	v_max_f32_e32 v63, 0, v63
	v_max_f32_e32 v56, 0, v56
	v_max_f32_e32 v57, 0, v57
	v_max_f32_e32 v58, 0, v58
	v_max_f32_e32 v59, 0, v59
	v_pk_mul_f32 v[60:61], v[60:61], v[60:61]
	v_pk_mul_f32 v[62:63], v[62:63], v[62:63]
	v_pk_mul_f32 v[56:57], v[56:57], v[56:57]
	v_pk_mul_f32 v[58:59], v[58:59], v[58:59]
	v_cvt_pk_bf16_f32 v60, v60, v61
	v_cvt_pk_bf16_f32 v61, v62, v63
	v_cvt_pk_bf16_f32 v62, v56, v57
	v_cvt_pk_bf16_f32 v63, v58, v59
	flat_store_dwordx4 v[150:151], v[60:63]
	v_max_f32_e32 v52, 0, v52
	v_max_f32_e32 v53, 0, v53
	v_max_f32_e32 v54, 0, v54
	v_max_f32_e32 v55, 0, v55
	v_max_f32_e32 v48, 0, v48
	v_max_f32_e32 v49, 0, v49
	v_max_f32_e32 v50, 0, v50
	v_max_f32_e32 v51, 0, v51
	v_pk_mul_f32 v[52:53], v[52:53], v[52:53]
	v_pk_mul_f32 v[54:55], v[54:55], v[54:55]
	v_pk_mul_f32 v[48:49], v[48:49], v[48:49]
	v_pk_mul_f32 v[50:51], v[50:51], v[50:51]
	v_cvt_pk_bf16_f32 v52, v52, v53
	v_cvt_pk_bf16_f32 v53, v54, v55
	v_cvt_pk_bf16_f32 v54, v48, v49
	v_cvt_pk_bf16_f32 v55, v50, v51
	flat_store_dwordx4 v[150:151], v[52:55] offset:256
	v_add_co_u32_e32 v150, vcc, 0x120000, v152
	s_nop 1
	v_addc_co_u32_e32 v151, vcc, 0, v153, vcc
	v_max_f32_e32 v44, 0, v44
	v_max_f32_e32 v45, 0, v45
	v_max_f32_e32 v46, 0, v46
	v_max_f32_e32 v47, 0, v47
	v_max_f32_e32 v40, 0, v40
	v_max_f32_e32 v41, 0, v41
	v_max_f32_e32 v42, 0, v42
	v_max_f32_e32 v43, 0, v43
	v_pk_mul_f32 v[44:45], v[44:45], v[44:45]
	v_pk_mul_f32 v[46:47], v[46:47], v[46:47]
	v_pk_mul_f32 v[40:41], v[40:41], v[40:41]
	v_pk_mul_f32 v[42:43], v[42:43], v[42:43]
	v_cvt_pk_bf16_f32 v44, v44, v45
	v_cvt_pk_bf16_f32 v45, v46, v47
	v_cvt_pk_bf16_f32 v46, v40, v41
	v_cvt_pk_bf16_f32 v47, v42, v43
	flat_store_dwordx4 v[150:151], v[44:47]
	v_max_f32_e32 v36, 0, v36
	v_max_f32_e32 v37, 0, v37
	v_max_f32_e32 v38, 0, v38
	v_max_f32_e32 v39, 0, v39
	v_max_f32_e32 v32, 0, v32
	v_max_f32_e32 v33, 0, v33
	v_max_f32_e32 v34, 0, v34
	v_max_f32_e32 v35, 0, v35
	v_pk_mul_f32 v[36:37], v[36:37], v[36:37]
	v_pk_mul_f32 v[38:39], v[38:39], v[38:39]
	v_pk_mul_f32 v[32:33], v[32:33], v[32:33]
	v_pk_mul_f32 v[34:35], v[34:35], v[34:35]
	v_cvt_pk_bf16_f32 v36, v36, v37
	v_cvt_pk_bf16_f32 v37, v38, v39
	v_cvt_pk_bf16_f32 v38, v32, v33
	v_cvt_pk_bf16_f32 v39, v34, v35
	flat_store_dwordx4 v[150:151], v[36:39] offset:256
	v_add_co_u32_e32 v150, vcc, 0x140000, v152
	s_nop 1
	v_addc_co_u32_e32 v151, vcc, 0, v153, vcc
	v_max_f32_e32 v28, 0, v28
	v_max_f32_e32 v29, 0, v29
	v_max_f32_e32 v30, 0, v30
	v_max_f32_e32 v31, 0, v31
	v_max_f32_e32 v24, 0, v24
	v_max_f32_e32 v25, 0, v25
	v_max_f32_e32 v26, 0, v26
	v_max_f32_e32 v27, 0, v27
	v_pk_mul_f32 v[28:29], v[28:29], v[28:29]
	v_pk_mul_f32 v[30:31], v[30:31], v[30:31]
	v_pk_mul_f32 v[24:25], v[24:25], v[24:25]
	v_pk_mul_f32 v[26:27], v[26:27], v[26:27]
	v_cvt_pk_bf16_f32 v28, v28, v29
	v_cvt_pk_bf16_f32 v29, v30, v31
	v_cvt_pk_bf16_f32 v30, v24, v25
	v_cvt_pk_bf16_f32 v31, v26, v27
	flat_store_dwordx4 v[150:151], v[28:31]
	v_max_f32_e32 v20, 0, v20
	v_max_f32_e32 v21, 0, v21
	v_max_f32_e32 v22, 0, v22
	v_max_f32_e32 v23, 0, v23
	v_max_f32_e32 v16, 0, v16
	v_max_f32_e32 v17, 0, v17
	v_max_f32_e32 v18, 0, v18
	v_max_f32_e32 v19, 0, v19
	v_pk_mul_f32 v[20:21], v[20:21], v[20:21]
	v_pk_mul_f32 v[22:23], v[22:23], v[22:23]
	v_pk_mul_f32 v[16:17], v[16:17], v[16:17]
	v_pk_mul_f32 v[18:19], v[18:19], v[18:19]
	v_cvt_pk_bf16_f32 v20, v20, v21
	v_cvt_pk_bf16_f32 v21, v22, v23
	v_cvt_pk_bf16_f32 v22, v16, v17
	v_cvt_pk_bf16_f32 v23, v18, v19
	flat_store_dwordx4 v[150:151], v[20:23] offset:256
	v_add_co_u32_e32 v150, vcc, 0x160000, v152
	s_nop 1
	v_addc_co_u32_e32 v151, vcc, 0, v153, vcc
	v_max_f32_e32 v12, 0, v12
	v_max_f32_e32 v13, 0, v13
	v_max_f32_e32 v14, 0, v14
	v_max_f32_e32 v15, 0, v15
	v_max_f32_e32 v8, 0, v8
	v_max_f32_e32 v9, 0, v9
	v_max_f32_e32 v10, 0, v10
	v_max_f32_e32 v11, 0, v11
	v_pk_mul_f32 v[12:13], v[12:13], v[12:13]
	v_pk_mul_f32 v[14:15], v[14:15], v[14:15]
	v_pk_mul_f32 v[8:9], v[8:9], v[8:9]
	v_pk_mul_f32 v[10:11], v[10:11], v[10:11]
	v_cvt_pk_bf16_f32 v12, v12, v13
	v_cvt_pk_bf16_f32 v13, v14, v15
	v_cvt_pk_bf16_f32 v14, v8, v9
	v_cvt_pk_bf16_f32 v15, v10, v11
	flat_store_dwordx4 v[150:151], v[12:15]
	v_max_f32_e32 v4, 0, v4
	v_max_f32_e32 v5, 0, v5
	v_max_f32_e32 v6, 0, v6
	v_max_f32_e32 v7, 0, v7
	v_max_f32_e32 v0, 0, v0
	v_max_f32_e32 v1, 0, v1
	v_max_f32_e32 v2, 0, v2
	v_max_f32_e32 v3, 0, v3
	v_pk_mul_f32 v[4:5], v[4:5], v[4:5]
	v_pk_mul_f32 v[6:7], v[6:7], v[6:7]
	v_pk_mul_f32 v[0:1], v[0:1], v[0:1]
	v_pk_mul_f32 v[2:3], v[2:3], v[2:3]
	v_cvt_pk_bf16_f32 v4, v4, v5
	v_cvt_pk_bf16_f32 v5, v6, v7
	v_cvt_pk_bf16_f32 v6, v0, v1
	v_cvt_pk_bf16_f32 v7, v2, v3
	s_andn2_b64 vcc, exec, s[4:5]
	s_mov_b64 s[4:5], -1
	flat_store_dwordx4 v[150:151], v[4:7] offset:256
	s_cbranch_vccnz .LBB0_1167
	s_andn2_b64 vcc, exec, s[0:1]
	s_cbranch_vccnz .LBB0_1166
	s_barrier
	s_branch .LBB0_1166
